# counting barrier plus: the second-to-last local arriver starts an L2 writeback early (not waited on) so the XCD leader's own writeback finds the L2 mostly clean
# baseline (speedup 1.0000x reference)
.LBB0_856:
	s_or_b64 exec, exec, s[2:3]
	v_cvt_f32_u32_e32 v5, v3
	s_waitcnt vmcnt(0)
	v_readfirstlane_b32 s2, v4
	v_sub_u32_e32 v4, 0, v3
	v_rcp_iflag_f32_e32 v5, v5
	v_add_u32_e32 v6, s2, v0
	v_mul_f32_e32 v5, 0x4f7ffffe, v5
	v_cvt_u32_f32_e32 v5, v5
	v_mul_lo_u32 v0, v4, v5
	v_mul_hi_u32 v0, v5, v0
	v_add_u32_e32 v0, v5, v0
	v_mul_hi_u32 v0, v6, v0
	v_mul_lo_u32 v4, v0, v3
	v_sub_u32_e32 v4, v6, v4
	v_add_u32_e32 v5, 1, v0
	v_cmp_ge_u32_e32 vcc, v4, v3
	s_nop 1
	v_cndmask_b32_e32 v0, v0, v5, vcc
	v_sub_u32_e32 v5, v4, v3
	v_cndmask_b32_e32 v4, v4, v5, vcc
	v_add_u32_e32 v5, 1, v0
	v_cmp_ge_u32_e32 vcc, v4, v3
	v_add_u32_e32 v4, 1, v6
	s_nop 0
	v_cndmask_b32_e32 v0, v0, v5, vcc
	v_mul_lo_u32 v5, v3, v0
	v_add_u32_e32 v3, v5, v3
	v_cmp_ne_u32_e32 vcc, v4, v3
	v_sub_u32_e32 v6, v3, v4
	v_cmp_eq_u32_e64 s[6:7], 1, v6
	s_cbranch_vccz .Lxb_leader
	s_and_b64 s[6:7], s[6:7], exec
	s_cbranch_scc0 .Lxb_poll
	buffer_wbl2 sc1
	s_branch .Lxb_poll
.Lxb_leader:
	buffer_wbl2 sc1
	v_readlane_b32 s6, v251, 54
	v_readlane_b32 s7, v251, 55
	s_waitcnt vmcnt(0)
	s_add_u32 s6, s6, 0x2200
	s_addc_u32 s7, s7, 0
	v_mov_b64_e32 v[4:5], s[6:7]
	global_atomic_add v[4:5], v228, off
	global_atomic_add v[4:5], v228, off offset:256
	global_atomic_add v[4:5], v228, off offset:512
	global_atomic_add v[4:5], v228, off offset:768
	global_atomic_add v[4:5], v228, off offset:1024
	global_atomic_add v[4:5], v228, off offset:1280
	global_atomic_add v[4:5], v228, off offset:1536
	global_atomic_add v[4:5], v228, off offset:1792
	global_atomic_add v[4:5], v228, off offset:2048
	global_atomic_add v[4:5], v228, off offset:2304
	global_atomic_add v[4:5], v228, off offset:2560
	global_atomic_add v[4:5], v228, off offset:2816
	global_atomic_add v[4:5], v228, off offset:3072
	global_atomic_add v[4:5], v228, off offset:3328
	global_atomic_add v[4:5], v228, off offset:3584
	global_atomic_add v[4:5], v228, off offset:3840
